# K bank fix + V staging thread map changed so each ds_write_b128 lane group writes 128 contiguous bytes (no 2-way bank conflict)
# speedup vs baseline: 1.0063x; 1.0063x over previous
.LBB0_338:
	s_or_b64 exec, exec, s[12:13]
	v_mov_b32_e32 v51, s43
	v_mov_b32_e32 v56, s42
	v_cmp_gt_i32_e64 s[12:13], 0, v185
	s_nop 1
	v_max_f32_e32 v57, v18, v18
	v_mov_b32_e32 v190, 0
	v_cndmask_b32_e64 v51, v51, v56, s[12:13]
	v_cndmask_b32_e64 v56, v51, 0, s[8:9]
	v_max_f32_e32 v51, v19, v19
	v_max_f32_e32 v51, v57, v51
	v_max3_f32 v51, v51, v20, v21
	v_max3_f32 v51, v51, v22, v23
	v_max3_f32 v51, v51, v24, v25
	v_max3_f32 v51, v51, v26, v27
	v_max3_f32 v51, v51, v28, v29
	v_max3_f32 v51, v51, v30, v31
	v_max3_f32 v51, v51, v32, v33
	v_max3_f32 v51, v51, v2, v3
	v_max3_f32 v51, v51, v4, v5
	v_max3_f32 v51, v51, v6, v7
	v_max3_f32 v51, v51, v8, v9
	v_max3_f32 v51, v51, v10, v11
	v_max3_f32 v51, v51, v12, v13
	v_max3_f32 v51, v51, v14, v15
	v_max3_f32 v51, v51, v16, v17
	v_mov_b32_e32 v57, v51
	s_nop 1
	v_permlane32_swap_b32_e32 v51, v57
	v_max_f32_e32 v57, v57, v57
	v_max_f32_e32 v51, v51, v51
	v_max_f32_e32 v51, v51, v57
	v_add_f32_e32 v57, v56, v51
	v_sub_f32_e32 v191, s43, v57
	v_sub_f32_e32 v190, 0, v57
	v_sub_f32_e32 v192, s42, v57
	v_mov_b32_e32 v176, 0
	v_readfirstlane_b32 s98, v185
	s_mov_b32 s99, 64
	v_sub_f32_e32 v56, v56, v57
	v_add_f32_e32 v3, v3, v56
	v_add_f32_e32 v2, v2, v56
	v_add_f32_e32 v4, v4, v56
	v_exp_f32_e32 v196, v3
	v_lshlrev_b32_e32 v3, 4, v55
	s_xor_b64 s[42:43], s[2:3], -1
	v_exp_f32_e32 v195, v2
	v_exp_f32_e32 v197, v4
	v_lshlrev_b32_e32 v2, 3, v55
	v_and_b32_e32 v3, 0xc0, v3
	v_lshlrev_b32_e32 v4, 1, v55
	v_and_or_b32 v3, v2, 24, v3
	v_and_b32_e32 v4, 32, v4
	v_and_b32_e32 v2, 0x100, v2
	s_cmp_lg_u32 0, -1
	v_or3_b32 v2, v3, v4, v2
	s_cselect_b32 s2, 0, 0
	v_add_u32_e32 v180, s2, v2
	s_addk_i32 s2, 0x4000
	v_add_u32_e32 v177, s2, v2
	v_add_lshl_u32 v2, v185, v53, 2
	v_ashrrev_i32_e32 v51, 31, v50
	v_add_f32_e32 v18, v18, v56
	v_add_f32_e32 v19, v19, v56
	v_add_f32_e32 v20, v20, v56
	v_add_f32_e32 v21, v21, v56
	v_add_f32_e32 v22, v22, v56
	v_add_f32_e32 v23, v23, v56
	v_add_f32_e32 v24, v24, v56
	v_add_f32_e32 v25, v25, v56
	v_add_f32_e32 v26, v26, v56
	v_add_f32_e32 v27, v27, v56
	v_add_f32_e32 v28, v28, v56
	v_add_f32_e32 v29, v29, v56
	v_add_f32_e32 v30, v30, v56
	v_add_f32_e32 v31, v31, v56
	v_add_f32_e32 v32, v32, v56
	v_add_f32_e32 v33, v33, v56
	v_add_f32_e32 v5, v5, v56
	v_add_f32_e32 v6, v6, v56
	v_add_f32_e32 v7, v7, v56
	v_add_f32_e32 v8, v8, v56
	v_add_f32_e32 v9, v9, v56
	v_add_f32_e32 v10, v10, v56
	v_add_f32_e32 v11, v11, v56
	v_add_f32_e32 v12, v12, v56
	v_add_f32_e32 v13, v13, v56
	v_add_f32_e32 v14, v14, v56
	v_add_f32_e32 v15, v15, v56
	v_add_f32_e32 v16, v16, v56
	v_add_f32_e32 v17, v17, v56
	v_sub_u32_e32 v2, v98, v2
	s_add_i32 s2, 0, 0x10c80
	v_exp_f32_e32 v199, v18
	v_exp_f32_e32 v201, v19
	v_exp_f32_e32 v202, v20
	v_exp_f32_e32 v205, v21
	v_exp_f32_e32 v207, v22
	v_exp_f32_e32 v209, v23
	v_exp_f32_e32 v211, v24
	v_exp_f32_e32 v213, v25
	v_exp_f32_e32 v215, v26
	v_exp_f32_e32 v216, v27
	v_exp_f32_e32 v217, v28
	v_exp_f32_e32 v218, v29
	v_exp_f32_e32 v221, v30
	v_exp_f32_e32 v222, v31
	v_exp_f32_e32 v223, v32
	v_exp_f32_e32 v224, v33
	v_exp_f32_e32 v198, v5
	v_exp_f32_e32 v200, v6
	v_exp_f32_e32 v203, v7
	v_exp_f32_e32 v204, v8
	v_exp_f32_e32 v206, v9
	v_exp_f32_e32 v208, v10
	v_exp_f32_e32 v210, v11
	v_exp_f32_e32 v212, v12
	v_exp_f32_e32 v214, v13
	v_exp_f32_e32 v150, v14
	v_exp_f32_e32 v151, v15
	v_exp_f32_e32 v152, v16
	v_exp_f32_e32 v153, v17
	v_add_u32_e32 v194, s2, v2
	v_lshl_add_u64 v[2:3], s[30:31], 0, v[50:51]
	s_waitcnt vmcnt(0)
	v_mad_u64_u32 v[4:5], s[2:3], v2, s49, 0
	v_and_b32_e32 v2, 15, v52
	v_mad_i32_i24 v3, v3, s49, v5
	v_lshl_or_b32 v2, v2, 4, v4
	s_mov_b32 s82, 0
	s_waitcnt vmcnt(3)
	ds_write_b128 v183, v[34:37] offset:16384
	s_waitcnt vmcnt(2)
	ds_write_b128 v184, v[38:41] offset:16384
	s_waitcnt vmcnt(0)
	s_mov_b64 s[100:101], exec
	s_and_b64 exec, exec, s[96:97]
	ds_write_b128 v181, v[42:45] offset:49152
	ds_write_b128 v182, v[46:49] offset:49152
	s_mov_b64 exec, s[100:101]
	v_mov_b32_e32 v181, v180
	s_mov_b32 s54, 0
	s_movk_i32 s55, 0x4000
	s_mov_b32 s56, 0x12000
	v_sub_u32_e32 v193, s81, v54
	s_mov_b32 s83, 2
	v_lshl_add_u64 v[160:161], s[40:41], 0, v[2:3]
	s_and_b32 s100, s42, 0x80
	v_lshrrev_b32_e32 v2, 3, v52
	v_sub_u32_e32 v3, v2, v50
	v_mul_u32_u24_e32 v3, 0x2800, v3
	v_and_b32_e32 v4, 8, v52
	v_lshlrev_b32_e32 v4, 4, v4
	v_sub_u32_e32 v3, v3, v4
	v_add_u32_e32 v3, s100, v3
	v_readfirstlane_b32 s101, v50
	v_readfirstlane_b32 s12, v160
	v_readfirstlane_b32 s13, v161
	s_nop 1
	v_subrev_u32_e32 v4, s101, v50
	v_mul_u32_u24_e32 v4, 0x2800, v4
	v_and_b32_e32 v160, 15, v52
	v_lshl_add_u32 v160, v160, 4, v4
	v_add_u32_e32 v161, 0x50000, v160
	v_add_u32_e32 v252, v160, v3
	v_bfe_u32 v5, v52, 2, 1
	v_bfe_u32 v6, v52, 5, 1
	v_lshl_add_u32 v6, v6, 1, v5
	v_mul_u32_u24_e32 v160, 0x2800, v6
	v_bfe_u32 v6, v52, 3, 2
	v_lshl_add_u32 v160, v6, 6, v160
	v_and_b32_e32 v7, 3, v52
	v_lshl_add_u32 v160, v7, 4, v160
	v_add_u32_e32 v161, 0x50000, v160
	v_lshrrev_b32_e32 v8, 5, v52
	v_lshl_add_u32 v8, v8, 1, v5
	v_lshrrev_b32_e32 v9, 3, v8
	v_lshlrev_b32_e32 v183, 11, v9
	v_lshl_add_u32 v183, v6, 9, v183
	v_and_b32_e32 v9, 7, v8
	v_lshl_add_u32 v183, v9, 6, v183
	v_lshl_add_u32 v183, v7, 4, v183
	v_and_b32_e32 v3, 7, v52
	v_and_b32_e32 v4, 7, v2
	v_xor_b32_e32 v3, v3, v4
	v_lshlrev_b32_e32 v3, 4, v3
	v_lshl_or_b32 v235, v2, 8, v3
	v_and_b32_e32 v4, 8, v2
	v_lshl_or_b32 v235, v4, 4, v235
	v_mov_b32_e32 v2, 0
	v_mov_b32_e32 v3, v176
	v_mov_b32_e32 v4, v176
	v_mov_b32_e32 v5, v176
	v_mov_b32_e32 v6, v176
	v_mov_b32_e32 v7, v176
	v_mov_b32_e32 v8, v176
	v_mov_b32_e32 v9, v176
	v_mov_b32_e32 v10, v176
	v_mov_b32_e32 v11, v176
	v_mov_b32_e32 v12, v176
	v_mov_b32_e32 v13, v176
	v_mov_b32_e32 v14, v176
	v_mov_b32_e32 v15, v176
	v_mov_b32_e32 v16, v176
	v_mov_b32_e32 v17, v176
	v_mov_b32_e32 v18, 0
	v_mov_b32_e32 v19, v176
	v_mov_b32_e32 v20, v176
	v_mov_b32_e32 v21, v176
	v_mov_b32_e32 v22, v176
	v_mov_b32_e32 v23, v176
	v_mov_b32_e32 v24, v176
	v_mov_b32_e32 v25, v176
	v_mov_b32_e32 v26, v176
	v_mov_b32_e32 v27, v176
	v_mov_b32_e32 v28, v176
	v_mov_b32_e32 v29, v176
	v_mov_b32_e32 v30, v176
	v_mov_b32_e32 v31, v176
	v_mov_b32_e32 v32, v176
	v_mov_b32_e32 v33, v176
	v_mov_b32_e32 v34, 0
	v_mov_b32_e32 v35, v176
	v_mov_b32_e32 v36, v176
	v_mov_b32_e32 v37, v176
	v_mov_b32_e32 v38, v176
	v_mov_b32_e32 v39, v176
	v_mov_b32_e32 v40, v176
	v_mov_b32_e32 v41, v176
	v_mov_b32_e32 v42, v176
	v_mov_b32_e32 v43, v176
	v_mov_b32_e32 v44, v176
	v_mov_b32_e32 v45, v176
	v_mov_b32_e32 v46, v176
	v_mov_b32_e32 v47, v176
	v_mov_b32_e32 v48, v176
	v_mov_b32_e32 v49, v176
	v_mov_b32_e32 v50, 0
	v_mov_b32_e32 v51, v176
	v_mov_b32_e32 v52, v176
	v_mov_b32_e32 v53, v176
	v_mov_b32_e32 v54, v176
	v_mov_b32_e32 v55, v176
	v_mov_b32_e32 v56, v176
	v_mov_b32_e32 v57, v176
	v_mov_b32_e32 v58, v176
	v_mov_b32_e32 v59, v176
	v_mov_b32_e32 v60, v176
	v_mov_b32_e32 v61, v176
	v_mov_b32_e32 v62, v176
	v_mov_b32_e32 v63, v176
	v_mov_b32_e32 v64, v176
	v_mov_b32_e32 v65, v176
	s_waitcnt lgkmcnt(0)
	s_barrier
	s_branch .LBB0_346
